# WIN/WOUT weight conversion of next layer moved into gate/up tail round: WGs 128-255 (idle in the half-empty 6th round) do it in two passes; down phase converts only WGU
# speedup vs baseline: 1.0067x; 1.0067x over previous
; __device__ __forceinline__ const float* ka_in(kaptr p, int i) { return *(const float* const __attribute__((address_space(4)))*)(p + 8 * i); }
; __device__ __forceinline__ void tr_load(float (&v)[32], const TrItem& t, int lane) {
; #pragma unroll
;     for (int i = 0; i < 32; ++i) { const int kk = 2 * i + (lane >> 5); v[i] = t.W[(size_t)(t.k0 + kk) * t.Nsrc + t.c0 + (lane & 31)]; }
; }
; __global__ void __launch_bounds__(NTHR, 2) fwd_mega(Args args_unused, int ph_lo, int ph_hi) {
;     ...
;             if ((L + 1) & 1) { conv_plain(ka_in(ka, 4) + (size_t)nj * D * DIFF_IN, D, DIFF_IN, (bf16*)(ws + WS_WIN), scr, gw, ngw, lane); conv_plain(ka_in(ka, 5) + (size_t)nj * D * D, D, D, (bf16*)(ws + WS_WOUT), scr, gw, ngw, lane); }
;             else { conv_plain(ka_in(ka, 2) + (size_t)nj * D * RET_IN, D, RET_IN, (bf16*)(ws + WS_WIN), scr, gw, ngw, lane); conv_plain(ka_in(ka, 3) + (size_t)nj * 2048 * D, 2048, D, (bf16*)(ws + WS_WOUT), scr, gw, ngw, lane); }
.LBB0_942:
	s_waitcnt vmcnt(0)
	v_readlane_b32 s56, v255, 4
	v_readlane_b32 s58, v255, 6
	v_readlane_b32 s52, v255, 8
	v_readlane_b32 s57, v255, 5
	v_readlane_b32 s59, v255, 7
	v_readlane_b32 s53, v255, 9
	v_readlane_b32 s55, v255, 10
	s_barrier
	v_readlane_b32 s5, v254, 0
	s_cmp_lt_i32 s16, 3
	s_cbranch_scc0 .Lcv_skip
	s_nop 3
	s_cmp_lt_u32 s5, 0x80
	s_cbranch_scc1 .Lcv_skip
	s_mov_b64 s[44:45], s[6:7]
	s_add_i32 s18, s16, 1
	s_waitcnt lgkmcnt(0)
	s_mov_b64 s[26:27], s[56:57]
	s_waitcnt vmcnt(0)
	v_mov_b32_e32 v0, v228
	v_readlane_b32 s5, v254, 0
	s_load_dwordx2 s[24:25], s[26:27], 0x68
	s_lshl_b32 s5, s5, 3
	v_readfirstlane_b32 s4, v0
	s_ashr_i32 s4, s4, 6
	s_add_i32 s17, s5, s4
	s_addk_i32 s17, 0xfc00
	s_lshl_b32 s4, s4, 14
	v_bfe_u32 v33, v0, 5, 1
	v_and_b32_e32 v1, 31, v0
	v_bfe_u32 v45, v0, 3, 3
	v_lshlrev_b32_e32 v0, 3, v0
	s_add_i32 s4, s4, 0
	v_lshlrev_b32_e32 v34, 2, v1
	v_mul_u32_u24_e32 v1, 0x84, v33
	v_and_b32_e32 v50, 56, v0
	s_ashr_i32 s28, s18, 1
	v_add3_u32 v44, s4, v34, v1
	v_mul_u32_u24_e32 v0, 0x84, v50
	v_lshlrev_b32_e32 v1, 2, v45
	s_ashr_i32 s29, s28, 31
	v_add3_u32 v46, s4, v0, v1
	v_readlane_b32 s4, v255, 11
	s_waitcnt lgkmcnt(0)
	s_add_u32 s30, s24, 0x200000
	v_readlane_b32 s5, v255, 12
	s_addc_u32 s31, s25, 0
	v_or_b32_e32 v47, 8, v45
	v_or_b32_e32 v48, 16, v45
	v_or_b32_e32 v49, 24, v45
	s_mov_b64 s[6:7], -1
	s_and_b64 vcc, exec, s[4:5]
	s_cbranch_vccz .LcvA_b1032
	s_cmpk_gt_i32 s17, 0xbff
	s_cbranch_scc1 .LcvA_b1022
	s_load_dwordx2 s[4:5], s[26:27], 0x10
	s_mul_i32 s7, s28, 0x1800000
	s_mul_hi_i32 s6, s28, 0x1800000
	v_mov_b32_e32 v35, v32
	s_waitcnt lgkmcnt(0)
	s_add_u32 s4, s4, s7
	s_addc_u32 s5, s5, s6
	v_lshl_add_u64 v[36:37], s[4:5], 0, v[34:35]
	s_mul_hi_i32 s4, s17, 0x2aaaaaab
	s_lshr_b32 s5, s4, 31
	s_ashr_i32 s4, s4, 5
	s_add_i32 s5, s4, s5
	s_mul_i32 s4, s5, 0xc0
	s_sub_i32 s4, s17, s4
	s_lshl_b32 s4, s4, 5
	v_lshl_or_b32 v35, s5, 6, v33
	s_ashr_i32 s5, s4, 31
	v_lshl_add_u64 v[38:39], s[4:5], 2, v[36:37]
	v_mad_i64_i32 v[0:1], s[4:5], v35, s54, v[38:39]
	global_load_dword v0, v[0:1], off
	v_or_b32_e32 v1, 2, v35
	v_mad_i64_i32 v[2:3], s[4:5], v1, s54, v[38:39]
	global_load_dword v1, v[2:3], off
	v_or_b32_e32 v2, 4, v35
	v_mad_i64_i32 v[2:3], s[4:5], v2, s54, v[38:39]
	global_load_dword v2, v[2:3], off
	v_or_b32_e32 v3, 6, v35
	v_mad_i64_i32 v[4:5], s[4:5], v3, s54, v[38:39]
	global_load_dword v3, v[4:5], off
	v_or_b32_e32 v4, 8, v35
	v_mad_i64_i32 v[4:5], s[4:5], v4, s54, v[38:39]
	global_load_dword v4, v[4:5], off
	v_or_b32_e32 v5, 10, v35
	v_mad_i64_i32 v[6:7], s[4:5], v5, s54, v[38:39]
	global_load_dword v5, v[6:7], off
	v_or_b32_e32 v6, 12, v35
	v_mad_i64_i32 v[6:7], s[4:5], v6, s54, v[38:39]
	global_load_dword v6, v[6:7], off
	v_or_b32_e32 v7, 14, v35
	v_mad_i64_i32 v[8:9], s[4:5], v7, s54, v[38:39]
	global_load_dword v7, v[8:9], off
	v_or_b32_e32 v8, 16, v35
	v_mad_i64_i32 v[8:9], s[4:5], v8, s54, v[38:39]
	global_load_dword v8, v[8:9], off
	v_or_b32_e32 v9, 18, v35
	v_mad_i64_i32 v[10:11], s[4:5], v9, s54, v[38:39]
	global_load_dword v9, v[10:11], off
	v_or_b32_e32 v10, 20, v35
	v_mad_i64_i32 v[10:11], s[4:5], v10, s54, v[38:39]
	global_load_dword v10, v[10:11], off
	v_or_b32_e32 v11, 22, v35
	v_mad_i64_i32 v[12:13], s[4:5], v11, s54, v[38:39]
	global_load_dword v11, v[12:13], off
	v_or_b32_e32 v12, 24, v35
	v_mad_i64_i32 v[12:13], s[4:5], v12, s54, v[38:39]
	global_load_dword v12, v[12:13], off
	v_or_b32_e32 v13, 26, v35
	v_mad_i64_i32 v[14:15], s[4:5], v13, s54, v[38:39]
	global_load_dword v13, v[14:15], off
	v_or_b32_e32 v14, 28, v35
	v_mad_i64_i32 v[14:15], s[4:5], v14, s54, v[38:39]
	global_load_dword v14, v[14:15], off
	v_or_b32_e32 v15, 30, v35
	v_mad_i64_i32 v[16:17], s[4:5], v15, s54, v[38:39]
	global_load_dword v15, v[16:17], off
	v_or_b32_e32 v16, 32, v35
	v_mad_i64_i32 v[16:17], s[4:5], v16, s54, v[38:39]
	global_load_dword v16, v[16:17], off
	v_or_b32_e32 v17, 34, v35
	v_mad_i64_i32 v[18:19], s[4:5], v17, s54, v[38:39]
	global_load_dword v17, v[18:19], off
	v_or_b32_e32 v18, 36, v35
	v_mad_i64_i32 v[18:19], s[4:5], v18, s54, v[38:39]
	global_load_dword v18, v[18:19], off
	v_or_b32_e32 v19, 38, v35
	v_mad_i64_i32 v[20:21], s[4:5], v19, s54, v[38:39]
	global_load_dword v19, v[20:21], off
	v_or_b32_e32 v20, 40, v35
	v_mad_i64_i32 v[20:21], s[4:5], v20, s54, v[38:39]
	global_load_dword v20, v[20:21], off
	v_or_b32_e32 v21, 42, v35
	v_mad_i64_i32 v[22:23], s[4:5], v21, s54, v[38:39]
	global_load_dword v21, v[22:23], off
	v_or_b32_e32 v22, 44, v35
	v_mad_i64_i32 v[22:23], s[4:5], v22, s54, v[38:39]
	global_load_dword v22, v[22:23], off
	v_or_b32_e32 v23, 46, v35
	v_mad_i64_i32 v[24:25], s[4:5], v23, s54, v[38:39]
	global_load_dword v23, v[24:25], off
	v_or_b32_e32 v24, 48, v35
	v_mad_i64_i32 v[24:25], s[4:5], v24, s54, v[38:39]
	global_load_dword v24, v[24:25], off
	v_or_b32_e32 v25, 50, v35
	v_mad_i64_i32 v[26:27], s[4:5], v25, s54, v[38:39]
	global_load_dword v25, v[26:27], off
	v_or_b32_e32 v26, 52, v35
	v_mad_i64_i32 v[26:27], s[4:5], v26, s54, v[38:39]
	global_load_dword v26, v[26:27], off
	v_or_b32_e32 v27, 54, v35
	v_mad_i64_i32 v[28:29], s[4:5], v27, s54, v[38:39]
	global_load_dword v27, v[28:29], off
	v_or_b32_e32 v28, 56, v35
	v_mad_i64_i32 v[28:29], s[4:5], v28, s54, v[38:39]
	global_load_dword v28, v[28:29], off
	v_or_b32_e32 v29, 58, v35
	v_mad_i64_i32 v[30:31], s[4:5], v29, s54, v[38:39]
	global_load_dword v29, v[30:31], off
	v_or_b32_e32 v30, 60, v35
	v_mad_i64_i32 v[30:31], s[4:5], v30, s54, v[38:39]
	global_load_dword v30, v[30:31], off
	v_or_b32_e32 v31, 62, v35
	v_mad_i64_i32 v[38:39], s[4:5], v31, s54, v[38:39]
	global_load_dword v31, v[38:39], off
	v_lshlrev_b32_e32 v38, 1, v50
	s_mov_b32 s4, s17
	s_branch .LcvA_b1017

; __device__ __forceinline__ const float* ka_in(kaptr p, int i) { return *(const float* const __attribute__((address_space(4)))*)(p + 8 * i); }
; __device__ __forceinline__ void tr_load(float (&v)[32], const TrItem& t, int lane) {
; #pragma unroll
;     for (int i = 0; i < 32; ++i) { const int kk = 2 * i + (lane >> 5); v[i] = t.W[(size_t)(t.k0 + kk) * t.Nsrc + t.c0 + (lane & 31)]; }
; }
; __global__ void __launch_bounds__(NTHR, 2) fwd_mega(Args args_unused, int ph_lo, int ph_hi) {
;     ...
;             if ((L + 1) & 1) { conv_plain(ka_in(ka, 4) + (size_t)nj * D * DIFF_IN, D, DIFF_IN, (bf16*)(ws + WS_WIN), scr, gw, ngw, lane); conv_plain(ka_in(ka, 5) + (size_t)nj * D * D, D, D, (bf16*)(ws + WS_WOUT), scr, gw, ngw, lane); }
;             else { conv_plain(ka_in(ka, 2) + (size_t)nj * D * RET_IN, D, RET_IN, (bf16*)(ws + WS_WIN), scr, gw, ngw, lane); conv_plain(ka_in(ka, 3) + (size_t)nj * 2048 * D, 2048, D, (bf16*)(ws + WS_WOUT), scr, gw, ngw, lane); }
.Lcv_passA_done:
	s_waitcnt lgkmcnt(0)
	s_mov_b64 s[26:27], s[56:57]
	s_waitcnt vmcnt(0)
	v_mov_b32_e32 v0, v228
	v_readlane_b32 s5, v254, 0
	s_load_dwordx2 s[24:25], s[26:27], 0x68
	s_lshl_b32 s5, s5, 3
	v_readfirstlane_b32 s4, v0
	s_ashr_i32 s4, s4, 6
	s_add_i32 s17, s5, s4
	s_lshl_b32 s4, s4, 14
	v_bfe_u32 v33, v0, 5, 1
	v_and_b32_e32 v1, 31, v0
	v_bfe_u32 v45, v0, 3, 3
	v_lshlrev_b32_e32 v0, 3, v0
	s_add_i32 s4, s4, 0
	v_lshlrev_b32_e32 v34, 2, v1
	v_mul_u32_u24_e32 v1, 0x84, v33
	v_and_b32_e32 v50, 56, v0
	s_ashr_i32 s28, s18, 1
	v_add3_u32 v44, s4, v34, v1
	v_mul_u32_u24_e32 v0, 0x84, v50
	v_lshlrev_b32_e32 v1, 2, v45
	s_ashr_i32 s29, s28, 31
	v_add3_u32 v46, s4, v0, v1
	v_readlane_b32 s4, v255, 11
	s_waitcnt lgkmcnt(0)
	s_add_u32 s30, s24, 0x200000
	v_readlane_b32 s5, v255, 12
	s_addc_u32 s31, s25, 0
	v_or_b32_e32 v47, 8, v45
	v_or_b32_e32 v48, 16, v45
	v_or_b32_e32 v49, 24, v45
	s_mov_b64 s[6:7], -1
	s_and_b64 vcc, exec, s[4:5]
	s_cbranch_vccz .LcvB_b1032
	s_cmpk_gt_i32 s17, 0xbff
	s_cbranch_scc1 .LcvB_b1022
	s_load_dwordx2 s[4:5], s[26:27], 0x10
	s_mul_i32 s7, s28, 0x1800000
	s_mul_hi_i32 s6, s28, 0x1800000
	v_mov_b32_e32 v35, v32
	s_waitcnt lgkmcnt(0)
	s_add_u32 s4, s4, s7
	s_addc_u32 s5, s5, s6
	v_lshl_add_u64 v[36:37], s[4:5], 0, v[34:35]
	s_mul_hi_i32 s4, s17, 0x2aaaaaab
	s_lshr_b32 s5, s4, 31
	s_ashr_i32 s4, s4, 5
	s_add_i32 s5, s4, s5
	s_mul_i32 s4, s5, 0xc0
	s_sub_i32 s4, s17, s4
	s_lshl_b32 s4, s4, 5
	v_lshl_or_b32 v35, s5, 6, v33
	s_ashr_i32 s5, s4, 31
	v_lshl_add_u64 v[38:39], s[4:5], 2, v[36:37]
	v_mad_i64_i32 v[0:1], s[4:5], v35, s54, v[38:39]
	global_load_dword v0, v[0:1], off
	v_or_b32_e32 v1, 2, v35
	v_mad_i64_i32 v[2:3], s[4:5], v1, s54, v[38:39]
	global_load_dword v1, v[2:3], off
	v_or_b32_e32 v2, 4, v35
	v_mad_i64_i32 v[2:3], s[4:5], v2, s54, v[38:39]
	global_load_dword v2, v[2:3], off
	v_or_b32_e32 v3, 6, v35
	v_mad_i64_i32 v[4:5], s[4:5], v3, s54, v[38:39]
	global_load_dword v3, v[4:5], off
	v_or_b32_e32 v4, 8, v35
	v_mad_i64_i32 v[4:5], s[4:5], v4, s54, v[38:39]
	global_load_dword v4, v[4:5], off
	v_or_b32_e32 v5, 10, v35
	v_mad_i64_i32 v[6:7], s[4:5], v5, s54, v[38:39]
	global_load_dword v5, v[6:7], off
	v_or_b32_e32 v6, 12, v35
	v_mad_i64_i32 v[6:7], s[4:5], v6, s54, v[38:39]
	global_load_dword v6, v[6:7], off
	v_or_b32_e32 v7, 14, v35
	v_mad_i64_i32 v[8:9], s[4:5], v7, s54, v[38:39]
	global_load_dword v7, v[8:9], off
	v_or_b32_e32 v8, 16, v35
	v_mad_i64_i32 v[8:9], s[4:5], v8, s54, v[38:39]
	global_load_dword v8, v[8:9], off
	v_or_b32_e32 v9, 18, v35
	v_mad_i64_i32 v[10:11], s[4:5], v9, s54, v[38:39]
	global_load_dword v9, v[10:11], off
	v_or_b32_e32 v10, 20, v35
	v_mad_i64_i32 v[10:11], s[4:5], v10, s54, v[38:39]
	global_load_dword v10, v[10:11], off
	v_or_b32_e32 v11, 22, v35
	v_mad_i64_i32 v[12:13], s[4:5], v11, s54, v[38:39]
	global_load_dword v11, v[12:13], off
	v_or_b32_e32 v12, 24, v35
	v_mad_i64_i32 v[12:13], s[4:5], v12, s54, v[38:39]
	global_load_dword v12, v[12:13], off
	v_or_b32_e32 v13, 26, v35
	v_mad_i64_i32 v[14:15], s[4:5], v13, s54, v[38:39]
	global_load_dword v13, v[14:15], off
	v_or_b32_e32 v14, 28, v35
	v_mad_i64_i32 v[14:15], s[4:5], v14, s54, v[38:39]
	global_load_dword v14, v[14:15], off
	v_or_b32_e32 v15, 30, v35
	v_mad_i64_i32 v[16:17], s[4:5], v15, s54, v[38:39]
	global_load_dword v15, v[16:17], off
	v_or_b32_e32 v16, 32, v35
	v_mad_i64_i32 v[16:17], s[4:5], v16, s54, v[38:39]
	global_load_dword v16, v[16:17], off
	v_or_b32_e32 v17, 34, v35
	v_mad_i64_i32 v[18:19], s[4:5], v17, s54, v[38:39]
	global_load_dword v17, v[18:19], off
	v_or_b32_e32 v18, 36, v35
	v_mad_i64_i32 v[18:19], s[4:5], v18, s54, v[38:39]
	global_load_dword v18, v[18:19], off
	v_or_b32_e32 v19, 38, v35
	v_mad_i64_i32 v[20:21], s[4:5], v19, s54, v[38:39]
	global_load_dword v19, v[20:21], off
	v_or_b32_e32 v20, 40, v35
	v_mad_i64_i32 v[20:21], s[4:5], v20, s54, v[38:39]
	global_load_dword v20, v[20:21], off
	v_or_b32_e32 v21, 42, v35
	v_mad_i64_i32 v[22:23], s[4:5], v21, s54, v[38:39]
	global_load_dword v21, v[22:23], off
	v_or_b32_e32 v22, 44, v35
	v_mad_i64_i32 v[22:23], s[4:5], v22, s54, v[38:39]
	global_load_dword v22, v[22:23], off
	v_or_b32_e32 v23, 46, v35
	v_mad_i64_i32 v[24:25], s[4:5], v23, s54, v[38:39]
	global_load_dword v23, v[24:25], off
	v_or_b32_e32 v24, 48, v35
	v_mad_i64_i32 v[24:25], s[4:5], v24, s54, v[38:39]
	global_load_dword v24, v[24:25], off
	v_or_b32_e32 v25, 50, v35
	v_mad_i64_i32 v[26:27], s[4:5], v25, s54, v[38:39]
	global_load_dword v25, v[26:27], off
	v_or_b32_e32 v26, 52, v35
	v_mad_i64_i32 v[26:27], s[4:5], v26, s54, v[38:39]
	global_load_dword v26, v[26:27], off
	v_or_b32_e32 v27, 54, v35
	v_mad_i64_i32 v[28:29], s[4:5], v27, s54, v[38:39]
	global_load_dword v27, v[28:29], off
	v_or_b32_e32 v28, 56, v35
	v_mad_i64_i32 v[28:29], s[4:5], v28, s54, v[38:39]
	global_load_dword v28, v[28:29], off
	v_or_b32_e32 v29, 58, v35
	v_mad_i64_i32 v[30:31], s[4:5], v29, s54, v[38:39]
	global_load_dword v29, v[30:31], off
	v_or_b32_e32 v30, 60, v35
	v_mad_i64_i32 v[30:31], s[4:5], v30, s54, v[38:39]
	global_load_dword v30, v[30:31], off
	v_or_b32_e32 v31, 62, v35
	v_mad_i64_i32 v[38:39], s[4:5], v31, s54, v[38:39]
	global_load_dword v31, v[38:39], off
	v_lshlrev_b32_e32 v38, 1, v50
	s_mov_b32 s4, s17
	s_branch .LcvB_b1017

; #define SEAM(k) do { if (IN(k) && IN((k) + 1)) { if (ph_hi < 0) grid.sync(); else xcd_barrier(xbar); } } while (0)
; __device__ __forceinline__ void xcd_barrier(const XcdBarrier& b) {
;     asm volatile("s_waitcnt vmcnt(0)" ::: "memory");
;     __syncthreads();
;     if (threadIdx.x == 0) {
;         unsigned* bar = b.bar;
;         __builtin_amdgcn_s_waitcnt(0);
;         unsigned nloc = b.st[0], nx = b.st[1];
;         if (nloc == 0u) { xcd_barrier_complete(bar, b.x, nloc, nx); b.st[0] = nloc; b.st[1] = nx; }
; __global__ void __launch_bounds__(NTHR, 2) fwd_mega(Args args_unused, int ph_lo, int ph_hi) {
;     ...
;         SEAM(pb + 4);
;         if (L + 1 < DEPTH && IN(pb + 5)) { PH_BEGIN
.Lcv_done:
	s_mov_b64 s[6:7], s[44:45]
.Lcv_skip:
.LBB0_943:
	s_add_i32 s4, s0, 6
	s_cmp_lt_i32 s4, s59
	s_cselect_b64 s[24:25], -1, 0
	s_and_b64 s[6:7], s[6:7], s[24:25]
	s_andn2_b64 vcc, exec, s[6:7]
	s_cbranch_vccnz .LBB0_1011
	s_mov_b64 s[6:7], -1
	s_and_b64 vcc, exec, s[52:53]
	s_cbranch_vccz .LBB0_998
	s_waitcnt vmcnt(0)
	s_waitcnt vmcnt(0) lgkmcnt(0)
	s_barrier
	s_mov_b64 s[6:7], exec
	v_readlane_b32 s18, v254, 3
	v_readlane_b32 s19, v254, 4
	s_and_b64 s[18:19], s[6:7], s[18:19]
	s_mov_b64 exec, s[18:19]
	s_cbranch_execz .LBB0_997
	v_readlane_b32 s5, v254, 63
	s_waitcnt vmcnt(0) expcnt(0) lgkmcnt(0)
	s_nop 0
	v_mov_b32_e32 v0, s5
	ds_read_b32 v2, v0
	v_readlane_b32 s5, v255, 0
	s_waitcnt lgkmcnt(0)
	v_cmp_ne_u32_e32 vcc, 0, v2
	v_mov_b32_e32 v0, s5
	ds_read_b32 v0, v0
	s_cbranch_vccnz .LBB0_961
	s_mov_b32 s5, 1
	s_branch .LBB0_949

; __device__ __forceinline__ const float* ka_in(kaptr p, int i) { return *(const float* const __attribute__((address_space(4)))*)(p + 8 * i); }
; __global__ void __launch_bounds__(NTHR, 2) fwd_mega(Args args_unused, int ph_lo, int ph_hi) {
;     ...
;         if (L + 1 < DEPTH && IN(pb + 5)) { PH_BEGIN
;             const int nj = (L + 1) >> 1;
;             if ((L + 1) & 1) { conv_plain(ka_in(ka, 4) + (size_t)nj * D * DIFF_IN, D, DIFF_IN, (bf16*)(ws + WS_WIN), scr, gw, ngw, lane); conv_plain(ka_in(ka, 5) + (size_t)nj * D * D, D, D, (bf16*)(ws + WS_WOUT), scr, gw, ngw, lane); }
;             else { conv_plain(ka_in(ka, 2) + (size_t)nj * D * RET_IN, D, RET_IN, (bf16*)(ws + WS_WIN), scr, gw, ngw, lane); conv_plain(ka_in(ka, 3) + (size_t)nj * 2048 * D, 2048, D, (bf16*)(ws + WS_WOUT), scr, gw, ngw, lane); }
;             conv_gu(ka_in(ka, 9) + (size_t)(L + 1) * D * FF, ka_in(ka, 10) + (size_t)(L + 1) * D * FF, (bf16*)(ws + WS_WGU), scr, gw, ngw, lane);
.LBB0_1011:
	s_add_i32 s18, s16, 1
	s_cmp_lt_i32 s16, 3
	s_cselect_b64 s[22:23], -1, 0
	s_cmp_gt_i32 s16, 2
	s_cselect_b64 s[20:21], -1, 0
	s_cmp_le_i32 s58, s4
	s_cselect_b64 s[4:5], -1, 0
	s_and_b64 s[40:41], s[4:5], s[24:25]
	s_and_b64 s[4:5], s[22:23], s[40:41]
	s_andn2_b64 vcc, exec, s[4:5]
	s_cbranch_vccnz .LBB0_1061
	s_waitcnt lgkmcnt(0)
	s_mov_b64 s[26:27], s[56:57]
	s_waitcnt vmcnt(0)
	v_mov_b32_e32 v0, v228
	v_readlane_b32 s5, v254, 0
	s_load_dwordx2 s[24:25], s[26:27], 0x68
	s_lshl_b32 s5, s5, 3
	v_readfirstlane_b32 s4, v0
	s_ashr_i32 s4, s4, 6
	s_add_i32 s17, s5, s4
	s_lshl_b32 s4, s4, 14
	v_bfe_u32 v33, v0, 5, 1
	v_and_b32_e32 v1, 31, v0
	v_bfe_u32 v45, v0, 3, 3
	v_lshlrev_b32_e32 v0, 3, v0
	s_add_i32 s4, s4, 0
	v_lshlrev_b32_e32 v34, 2, v1
	v_mul_u32_u24_e32 v1, 0x84, v33
	v_and_b32_e32 v50, 56, v0
	s_ashr_i32 s28, s18, 1
	v_add3_u32 v44, s4, v34, v1
	v_mul_u32_u24_e32 v0, 0x84, v50
	v_lshlrev_b32_e32 v1, 2, v45
	s_ashr_i32 s29, s28, 31
	v_add3_u32 v46, s4, v0, v1
	v_readlane_b32 s4, v255, 11
	s_waitcnt lgkmcnt(0)
	s_add_u32 s30, s24, 0x200000
	v_readlane_b32 s5, v255, 12
	s_addc_u32 s31, s25, 0
	v_or_b32_e32 v47, 8, v45
	v_or_b32_e32 v48, 16, v45
	v_or_b32_e32 v49, 24, v45
	s_mov_b64 s[6:7], -1
	s_and_b64 vcc, exec, s[4:5]
	s_branch .LBB0_1051
